# attention tile head: sub-step 0 LDS fragment reads issued first, next-tile global load block moved into their latency shadow (on top of the barrier placement before the 3rd P.V MFMA)
# baseline (speedup 1.0000x reference)
; #define MFMA32(a, b, c) __builtin_amdgcn_mfma_f32_32x32x16_bf16((a), (b), (c), 0, 0, 0)
; __device__ __forceinline__ void attn_phase(const Args& a, int l, bool with_ctx, unsigned char* lds) {
;     ...
;         for (int t = 0; t < nt; ++t) {
;             const int cur = t & 1;
;             if (t + 1 < nt) { k0 = *(const u32x4*)(Kg0 + (size_t)(t + 1) * 64 * 64); k1 = *(const u32x4*)(Kg1 + (size_t)(t + 1) * 64 * 64);
;                               v0 = *(const u32x4*)(Vg0 + (t + 1) * 64); v1 = *(const u32x4*)(Vg1 + (t + 1) * 64); }
; #pragma unroll
;             for (int sub = 0; sub < 2; ++sub) {
;                 const unsigned char* kb = lds + cur * BUF + c * 9216 + (32 * sub + r32) * 144 + hi * 16;
;                 const unsigned char* vb = lds + cur * BUF + KT + r32 * 144 + 64 * sub + hi * 16;
;                 bf16x8 kf[4], vf[8];
; #pragma unroll
;                 for (int d0 = 0; d0 < 4; ++d0) kf[d0] = *(const bf16x8*)(kb + d0 * 32);
; #pragma unroll
;                 for (int j = 0; j < 4; ++j) { vf[2 * j] = *(const bf16x8*)(vb + j * 32 * 144); vf[2 * j + 1] = *(const bf16x8*)(vb + j * 32 * 144 + 32); }
;                 __builtin_amdgcn_sched_barrier(0);
;                 f32x16 S;
; #pragma unroll
;                 for (int r = 0; r < 16; ++r) S[r] = negm;
; #pragma unroll
;                 for (int d0 = 0; d0 < 4; ++d0) S = MFMA32(kf[d0], qf[d0], S);
;                 float mx = S[0];
; #pragma unroll
;                 for (int r = 1; r < 16; ++r) mx = fmaxf(mx, S[r]);
;                 if (first || __any(mx > 8.f)) {
;                     mx = fmaxf(mx, __shfl_xor(mx, 32));
;                     const float dl = first ? mx : fmaxf(mx, 0.f); const float alpha = first ? 1.f : __builtin_amdgcn_exp2f(-dl); negm -= dl; lrun *= alpha; first = false;
; #pragma unroll
;                     for (int r = 0; r < 16; ++r) S[r] -= dl;
; #pragma unroll
;                     for (int j = 0; j < 4; ++j)
; #pragma unroll
;                         for (int r = 0; r < 16; ++r) O[j][r] *= alpha;
;                 }
.LBB0_408:
	s_and_b32 s15, s15, 1
	s_mul_i32 s22, s15, 0x9000
	s_add_i32 s22, s22, 0
	v_add3_u32 v67, s22, v178, v160
	v_add_u32_e32 v68, s22, v179
	v_add_u32_e32 v185, v67, v179
	v_add_u32_e32 v184, v68, v160
	ds_read_b128 v[214:217], v185
	ds_read_b128 v[218:221], v185 offset:32
	ds_read_b128 v[222:225], v185 offset:64
	ds_read_b128 v[226:229], v185 offset:96
	ds_read_b128 v[140:143], v184 offset:18432
	ds_read_b128 v[128:131], v184 offset:18464
	ds_read_b128 v[144:147], v184 offset:23040
	ds_read_b128 v[116:119], v184 offset:23072
	ds_read_b128 v[136:139], v184 offset:27648
	ds_read_b128 v[120:123], v184 offset:27680
	ds_read_b128 v[132:135], v184 offset:32256
	ds_read_b128 v[124:127], v184 offset:32288
	s_cmp_ge_u32 s14, s7
	s_cbranch_scc1 .Lattn_nold
	v_lshl_add_u64 v[68:69], v[172:173], 0, v[154:155]
	v_add_co_u32_e32 v72, vcc, 0x1e504000, v68
	v_lshl_add_u64 v[70:71], v[174:175], 0, v[154:155]
	s_nop 0
	v_addc_co_u32_e32 v73, vcc, 0, v69, vcc
	v_add_co_u32_e32 v68, vcc, 0x1e58c000, v68
	s_nop 1
	v_addc_co_u32_e32 v69, vcc, 0, v69, vcc
	global_load_dwordx4 v[100:103], v[72:73], off
	global_load_dwordx4 v[104:107], v[68:69], off
	v_add_co_u32_e32 v68, vcc, 0x1f600000, v70
	s_nop 1
	v_addc_co_u32_e32 v69, vcc, 0, v71, vcc
	v_add_co_u32_e32 v70, vcc, 0x1f688000, v70
	s_nop 1
	v_addc_co_u32_e32 v71, vcc, 0, v71, vcc
	global_load_dwordx4 v[108:111], v[68:69], off offset:256
	global_load_dwordx4 v[112:115], v[70:71], off offset:256
.Lattn_nold:
	s_waitcnt lgkmcnt(11)
	s_nop 0
	v_mfma_f32_32x32x16_bf16 v[68:83], v[214:217], v[84:87], v[230:245]
	s_waitcnt lgkmcnt(10)
	v_mfma_f32_32x32x16_bf16 v[68:83], v[218:221], v[88:91], v[68:83]
	s_waitcnt lgkmcnt(9)
	v_mfma_f32_32x32x16_bf16 v[68:83], v[222:225], v[92:95], v[68:83]
	s_waitcnt lgkmcnt(8)
	v_mfma_f32_32x32x16_bf16 v[68:83], v[226:229], v[96:99], v[68:83]
	s_nop 11
	v_max_f32_e32 v67, v69, v69
	v_max_f32_e32 v186, v68, v68
	v_max_f32_e32 v67, v186, v67
	v_max3_f32 v67, v67, v70, v71
	v_max3_f32 v67, v67, v72, v73
	v_max3_f32 v67, v67, v74, v75
	v_max3_f32 v67, v67, v76, v77
	v_max3_f32 v67, v67, v78, v79
	v_max3_f32 v67, v67, v80, v81
	v_max3_f32 v67, v67, v82, v83
	v_cmp_lt_f32_e32 vcc, s68, v67
	s_cbranch_vccz .LBB0_410
	ds_bpermute_b32 v186, v180, v67
	s_waitcnt lgkmcnt(0)
	v_max3_f32 v186, v67, v186, 0
	v_exp_f32_e64 v214, -v186
	v_sub_f32_e32 v66, v66, v186
	v_mov_b32_e32 v230, v66
	v_mov_b32_e32 v231, v66
	v_mov_b32_e32 v232, v66
	v_mov_b32_e32 v233, v66
	v_mov_b32_e32 v234, v66
	v_mov_b32_e32 v235, v66
	v_mov_b32_e32 v236, v66
	v_mov_b32_e32 v237, v66
	v_mov_b32_e32 v238, v66
	v_mov_b32_e32 v239, v66
	v_mov_b32_e32 v240, v66
	v_mov_b32_e32 v241, v66
	v_mov_b32_e32 v242, v66
	v_mov_b32_e32 v243, v66
	v_mov_b32_e32 v244, v66
	v_mov_b32_e32 v245, v66
	v_pk_add_f32 v[68:69], v[68:69], v[186:187] op_sel_hi:[1,0] neg_lo:[0,1] neg_hi:[0,1]
	v_pk_add_f32 v[70:71], v[70:71], v[186:187] op_sel_hi:[1,0] neg_lo:[0,1] neg_hi:[0,1]
	v_pk_add_f32 v[72:73], v[72:73], v[186:187] op_sel_hi:[1,0] neg_lo:[0,1] neg_hi:[0,1]
	v_pk_add_f32 v[74:75], v[74:75], v[186:187] op_sel_hi:[1,0] neg_lo:[0,1] neg_hi:[0,1]
	v_pk_add_f32 v[76:77], v[76:77], v[186:187] op_sel_hi:[1,0] neg_lo:[0,1] neg_hi:[0,1]
	v_pk_add_f32 v[78:79], v[78:79], v[186:187] op_sel_hi:[1,0] neg_lo:[0,1] neg_hi:[0,1]
	v_pk_add_f32 v[80:81], v[80:81], v[186:187] op_sel_hi:[1,0] neg_lo:[0,1] neg_hi:[0,1]
	v_pk_add_f32 v[82:83], v[82:83], v[186:187] op_sel_hi:[1,0] neg_lo:[0,1] neg_hi:[0,1]
	v_pk_mul_f32 v[64:65], v[64:65], v[214:215] op_sel_hi:[1,0]
	v_pk_mul_f32 v[62:63], v[62:63], v[214:215] op_sel_hi:[1,0]
	v_pk_mul_f32 v[60:61], v[60:61], v[214:215] op_sel_hi:[1,0]
	v_pk_mul_f32 v[58:59], v[58:59], v[214:215] op_sel_hi:[1,0]
	v_pk_mul_f32 v[56:57], v[56:57], v[214:215] op_sel_hi:[1,0]
	v_pk_mul_f32 v[54:55], v[54:55], v[214:215] op_sel_hi:[1,0]
	v_pk_mul_f32 v[52:53], v[52:53], v[214:215] op_sel_hi:[1,0]
	v_pk_mul_f32 v[50:51], v[50:51], v[214:215] op_sel_hi:[1,0]
	v_pk_mul_f32 v[48:49], v[48:49], v[214:215] op_sel_hi:[1,0]
	v_pk_mul_f32 v[46:47], v[46:47], v[214:215] op_sel_hi:[1,0]
	v_pk_mul_f32 v[44:45], v[44:45], v[214:215] op_sel_hi:[1,0]
	v_pk_mul_f32 v[42:43], v[42:43], v[214:215] op_sel_hi:[1,0]
	v_pk_mul_f32 v[40:41], v[40:41], v[214:215] op_sel_hi:[1,0]
	v_pk_mul_f32 v[38:39], v[38:39], v[214:215] op_sel_hi:[1,0]
	v_pk_mul_f32 v[36:37], v[36:37], v[214:215] op_sel_hi:[1,0]
	v_pk_mul_f32 v[34:35], v[34:35], v[214:215] op_sel_hi:[1,0]
	v_pk_mul_f32 v[32:33], v[32:33], v[214:215] op_sel_hi:[1,0]
	v_pk_mul_f32 v[30:31], v[30:31], v[214:215] op_sel_hi:[1,0]
	v_pk_mul_f32 v[28:29], v[28:29], v[214:215] op_sel_hi:[1,0]
	v_pk_mul_f32 v[26:27], v[26:27], v[214:215] op_sel_hi:[1,0]
	v_pk_mul_f32 v[24:25], v[24:25], v[214:215] op_sel_hi:[1,0]
	v_pk_mul_f32 v[22:23], v[22:23], v[214:215] op_sel_hi:[1,0]
	v_pk_mul_f32 v[20:21], v[20:21], v[214:215] op_sel_hi:[1,0]
	v_pk_mul_f32 v[18:19], v[18:19], v[214:215] op_sel_hi:[1,0]
	v_pk_mul_f32 v[16:17], v[16:17], v[214:215] op_sel_hi:[1,0]
	v_pk_mul_f32 v[14:15], v[14:15], v[214:215] op_sel_hi:[1,0]
	v_pk_mul_f32 v[12:13], v[12:13], v[214:215] op_sel_hi:[1,0]
	v_pk_mul_f32 v[10:11], v[10:11], v[214:215] op_sel_hi:[1,0]
	v_pk_mul_f32 v[8:9], v[8:9], v[214:215] op_sel_hi:[1,0]
	v_pk_mul_f32 v[6:7], v[6:7], v[214:215] op_sel_hi:[1,0]
	v_pk_mul_f32 v[4:5], v[4:5], v[214:215] op_sel_hi:[1,0]
	v_pk_mul_f32 v[2:3], v[2:3], v[214:215] op_sel_hi:[1,0]
	v_mul_f32_e32 v171, v171, v214
